# v25prio
# speedup vs baseline: 1.0024x; 1.0024x over previous
.LBB0_119:
	s_cmp_gt_i32 s3, 1
	s_cbranch_scc0 .LBB0_299
	s_load_dwordx2 s[20:21], s[0:1], 0xc8
	s_waitcnt lgkmcnt(0)
	s_add_u32 s22, s20, 0x2b24000
	s_addc_u32 s23, s21, 0
	s_add_u32 s56, s20, 0x33f27800
	s_addc_u32 s68, s21, 0
	s_add_u32 s69, s20, 0xaf27800
	s_addc_u32 s71, s21, 0
	s_add_u32 s84, s20, 0x27b27800
	s_addc_u32 s85, s21, 0
	s_add_u32 s86, s20, 0x1b727800
	s_addc_u32 s87, s21, 0
	s_add_u32 s88, s20, 0x13327800
	s_addc_u32 s89, s21, 0
	s_add_u32 s96, s20, 0x2480000
	s_addc_u32 s97, s21, 0
	s_add_u32 s75, s20, 0x2fb27800
	s_addc_u32 s91, s21, 0
	s_add_u32 s35, s20, 0x2880000
	s_addc_u32 s36, s21, 0
	v_readfirstlane_b32 s6, v208
	s_nop 3
	s_lshr_b32 s6, s6, 6
	s_cmp_lt_u32 s6, 4
	s_cbranch_scc1 .Lprio2_done
	s_setprio 1
.Lprio2_done:
	s_branch .LBB0_124
.LBB0_121:
	s_or_b64 exec, exec, s[6:7]
